# staging loop peeled: first two and last four iterations emitted separately, no per-iteration range checks
# speedup vs baseline: 1.0105x; 1.0105x over previous
.Lsc_G:
	v_add_u32_e32 v1, 0xffffff00, v173
	v_lshrrev_b32_e32 v2, 3, v1
	v_and_b32_e32 v3, 7, v1
	s_and_b32 s8, s4, 7
	s_bfe_u32 s10, s4, 0x20003
	s_lshr_b32 s11, s4, 7
	s_bfe_u32 s9, s4, 0x20005
	s_lshl_b32 s9, s9, 13
	v_readlane_b32 s50, v242, 0
	v_readlane_b32 s51, v242, 1
	v_readlane_b32 s16, v242, 62
	s_load_dwordx4 s[12:15], s[50:51], 0x68
	s_add_u32 s36, s90, 0x5e00000
	s_addc_u32 s37, s91, 0
	s_add_u32 s38, s90, 0x7e00000
	s_addc_u32 s39, s91, 0
	s_add_u32 s44, s90, 0x9e00000
	s_addc_u32 s45, s91, 0
	s_add_u32 s46, s90, 0x1c00000
	s_addc_u32 s47, s91, 0
	s_lshl_b32 s68, s11, 25
	s_add_u32 s69, s68, 0x13e00000
	s_add_u32 s40, s90, s69
	s_addc_u32 s41, s91, 0
	s_add_u32 s69, s68, 0x17e00000
	s_add_u32 s42, s90, s69
	s_addc_u32 s43, s91, 0
	s_lshl_b32 s68, s11, 26
	s_add_u32 s68, s68, 0xbe00000
	s_add_u32 s48, s90, s68
	s_addc_u32 s49, s91, 0
	s_cmp_eq_u32 s11, 0
	s_mov_b32 s54, 0x8000
	s_movk_i32 s55, 0x400
	s_mov_b32 s64, 0x10000
	s_cselect_b32 s54, s54, 0xffff8000
	s_cselect_b32 s55, s55, 0xfffffc00
	s_cselect_b32 s64, s64, 0xffff0000
	s_cselect_b64 vcc, -1, 0
	v_sub_u32_e32 v4, 0x1fff, v2
	s_nop 3
	v_cndmask_b32_e32 v4, v4, v2, vcc
	v_add_u32_e32 v4, s9, v4
	s_lshl_b32 s68, s8, 7
	v_lshlrev_b32_e32 v5, 10, v4
	v_lshl_add_u32 v5, v3, 3, v5
	v_add_u32_e32 v5, s68, v5
	s_lshl_b32 s69, s8, 2
	v_lshlrev_b32_e32 v6, 5, v4
	v_add_u32_e32 v6, s69, v6
	s_lshl_b32 s69, s10, 5
	s_add_i32 s69, s69, s68
	v_lshlrev_b32_e32 v9, 10, v4
	v_lshl_add_u32 v9, v3, 2, v9
	v_add_u32_e32 v9, s69, v9
	s_lshl_b32 s69, s69, 1
	v_lshlrev_b32_e32 v7, 11, v4
	v_lshl_add_u32 v7, v3, 3, v7
	v_add_u32_e32 v7, s69, v7
	v_mul_u32_u24_e32 v8, 1024, v2
	v_lshl_add_u32 v8, v3, 4, v8
	v_add_u32_e32 v138, 512, v8
	v_add_u32_e32 v140, 35328, v8
	v_add_u32_e32 v152, -4, v0
	v_lshlrev_b32_e32 v152, 12, v152
	v_add_u32_e32 v152, 107072, v152
	v_and_b32_e32 v156, 7, v2
	v_lshlrev_b32_e32 v153, 8, v156
	v_lshl_add_u32 v153, v3, 4, v153
	v_add_u32_e32 v153, v152, v153
	v_and_b32_e32 v154, 63, v1
	v_lshl_add_u32 v154, v154, 2, v152
	v_add_u32_e32 v155, 2048, v154
	v_add_u32_e32 v139, -1, v2
	v_mul_u32_u24_e32 v139, 1024, v139
	v_lshl_add_u32 v139, v3, 4, v139
	v_add_u32_e32 v141, 35328, v139
	v_add_u32_e32 v139, 512, v139
	v_cmp_eq_u32_e32 vcc, 0, v2
	s_nop 1
	v_cndmask_b32_e32 v139, v139, v152, vcc
	v_cndmask_b32_e32 v141, v141, v152, vcc
	v_lshrrev_b32_e32 v158, 3, v2
	v_lshlrev_b32_e32 v158, 8, v158
	v_lshl_add_u32 v158, v3, 4, v158
	v_add_u32_e32 v159, 33792, v158
	v_add_u32_e32 v158, 32768, v158
	v_mul_u32_u24_e32 v142, 288, v3
	v_lshl_add_u32 v142, v2, 2, v142
	v_add_u32_e32 v143, 71936, v142
	v_add_u32_e32 v142, 69632, v142
	v_lshlrev_b32_e32 v11, 9, v2
	v_lshl_add_u32 v11, v3, 6, v11
	v_add_u32_e32 v11, 74240, v11
	s_lshl_b32 s69, s8, 6
	s_add_i32 s69, s69, s16
	v_lshl_add_u32 v106, v3, 2, s69
	v_lshlrev_b32_e32 v106, 2, v106
	s_waitcnt lgkmcnt(0)
	global_load_dwordx4 v[12:15], v106, s[12:13]
	global_load_dwordx4 v[16:19], v106, s[12:13] offset:128
	global_load_dwordx4 v[20:23], v106, s[14:15]
	global_load_dwordx4 v[24:27], v106, s[14:15] offset:128
	global_load_dwordx2 v[28:29], v5, s[36:37]
	global_load_dwordx2 v[30:31], v5, s[36:37] offset:64
	global_load_dwordx2 v[32:33], v5, s[38:39]
	global_load_dwordx2 v[34:35], v5, s[38:39] offset:64
	global_load_dwordx2 v[36:37], v5, s[40:41]
	global_load_dwordx2 v[38:39], v5, s[40:41] offset:64
	global_load_dwordx2 v[40:41], v5, s[42:43]
	global_load_dwordx2 v[42:43], v5, s[42:43] offset:64
	global_load_dword v44, v6, s[46:47]
	global_load_dword v45, v9, s[44:45]
	v_add_u32_e32 v5, s54, v5
	v_add_u32_e32 v6, s55, v6
	v_add_u32_e32 v9, s54, v9
	global_load_dwordx2 v[46:47], v5, s[36:37]
	global_load_dwordx2 v[48:49], v5, s[36:37] offset:64
	global_load_dwordx2 v[50:51], v5, s[38:39]
	global_load_dwordx2 v[52:53], v5, s[38:39] offset:64
	global_load_dwordx2 v[54:55], v5, s[40:41]
	global_load_dwordx2 v[56:57], v5, s[40:41] offset:64
	global_load_dwordx2 v[58:59], v5, s[42:43]
	global_load_dwordx2 v[60:61], v5, s[42:43] offset:64
	global_load_dword v62, v6, s[46:47]
	global_load_dword v63, v9, s[44:45]
	v_add_u32_e32 v5, s54, v5
	v_add_u32_e32 v6, s55, v6
	v_add_u32_e32 v9, s54, v9
	v_cmp_eq_u32_e64 s[12:13], 0, v156
	v_cmp_eq_u32_e64 s[14:15], 7, v156
	s_mov_b32 s6, 0
	v_mov_b32_e32 v144, 107024
	v_mov_b32_e32 v145, v164
	v_mov_b32_e32 v146, 0
	s_waitcnt vmcnt(10)
	v_lshlrev_b32_e32 v64, 16, v36
	v_and_b32_e32 v65, 0xffff0000, v36
	v_mul_f32_e32 v64, 0x3fb8aa3b, v64
	v_mul_f32_e32 v65, 0x3fb8aa3b, v65
	v_lshlrev_b32_e32 v66, 16, v37
	v_and_b32_e32 v67, 0xffff0000, v37
	v_mul_f32_e32 v66, 0x3fb8aa3b, v66
	v_mul_f32_e32 v67, 0x3fb8aa3b, v67
	v_lshlrev_b32_e32 v68, 16, v38
	v_and_b32_e32 v69, 0xffff0000, v38
	v_mul_f32_e32 v68, 0x3fb8aa3b, v68
	v_mul_f32_e32 v69, 0x3fb8aa3b, v69
	v_lshlrev_b32_e32 v70, 16, v39
	v_and_b32_e32 v71, 0xffff0000, v39
	v_mul_f32_e32 v70, 0x3fb8aa3b, v70
	v_mul_f32_e32 v71, 0x3fb8aa3b, v71
	ds_write_b128 v153, v[64:67]
	ds_write_b128 v153, v[68:71] offset:128
	s_waitcnt lgkmcnt(0)
	ds_read_b32 v124, v154 offset:0
	ds_read_b32 v125, v154 offset:256
	ds_read_b32 v126, v154 offset:512
	ds_read_b32 v127, v154 offset:768
	ds_read_b32 v128, v154 offset:1024
	ds_read_b32 v129, v154 offset:1280
	ds_read_b32 v130, v154 offset:1536
	ds_read_b32 v131, v154 offset:1792
	v_lshlrev_b32_e32 v108, 16, v32
	v_and_b32_e32 v109, 0xffff0000, v32
	v_lshlrev_b32_e32 v110, 16, v40
	v_and_b32_e32 v111, 0xffff0000, v40
	v_lshlrev_b32_e32 v96, 16, v28
	v_and_b32_e32 v97, 0xffff0000, v28
	v_pk_add_f32 v[112:113], v[110:111], -1.0 op_sel_hi:[1,0]
	v_pk_mul_f32 v[114:115], v[12:13], v[108:109]
	v_pk_fma_f32 v[112:113], v[20:21], v[112:113], 1.0 op_sel_hi:[1,1,0]
	v_pk_mul_f32 v[88:89], v[44:45], v[114:115] op_sel_hi:[0,1]
	v_pk_mul_f32 v[72:73], v[112:113], v[108:109]
	v_pk_mul_f32 v[80:81], v[88:89], v[110:111]
	v_lshlrev_b32_e32 v108, 16, v33
	v_and_b32_e32 v109, 0xffff0000, v33
	v_lshlrev_b32_e32 v110, 16, v41
	v_and_b32_e32 v111, 0xffff0000, v41
	v_lshlrev_b32_e32 v98, 16, v29
	v_and_b32_e32 v99, 0xffff0000, v29
	v_pk_add_f32 v[112:113], v[110:111], -1.0 op_sel_hi:[1,0]
	v_pk_mul_f32 v[114:115], v[14:15], v[108:109]
	v_pk_fma_f32 v[112:113], v[22:23], v[112:113], 1.0 op_sel_hi:[1,1,0]
	v_pk_mul_f32 v[90:91], v[44:45], v[114:115] op_sel_hi:[0,1]
	v_pk_mul_f32 v[74:75], v[112:113], v[108:109]
	v_pk_mul_f32 v[82:83], v[90:91], v[110:111]
	v_lshlrev_b32_e32 v108, 16, v34
	v_and_b32_e32 v109, 0xffff0000, v34
	v_lshlrev_b32_e32 v110, 16, v42
	v_and_b32_e32 v111, 0xffff0000, v42
	v_lshlrev_b32_e32 v100, 16, v30
	v_and_b32_e32 v101, 0xffff0000, v30
	v_pk_add_f32 v[112:113], v[110:111], -1.0 op_sel_hi:[1,0]
	v_pk_mul_f32 v[114:115], v[16:17], v[108:109]
	v_pk_fma_f32 v[112:113], v[24:25], v[112:113], 1.0 op_sel_hi:[1,1,0]
	v_pk_mul_f32 v[92:93], v[44:45], v[114:115] op_sel_hi:[0,1]
	v_pk_mul_f32 v[76:77], v[112:113], v[108:109]
	v_pk_mul_f32 v[84:85], v[92:93], v[110:111]
	v_lshlrev_b32_e32 v108, 16, v35
	v_and_b32_e32 v109, 0xffff0000, v35
	v_lshlrev_b32_e32 v110, 16, v43
	v_and_b32_e32 v111, 0xffff0000, v43
	v_lshlrev_b32_e32 v102, 16, v31
	v_and_b32_e32 v103, 0xffff0000, v31
	v_pk_add_f32 v[112:113], v[110:111], -1.0 op_sel_hi:[1,0]
	v_pk_mul_f32 v[114:115], v[18:19], v[108:109]
	v_pk_fma_f32 v[112:113], v[26:27], v[112:113], 1.0 op_sel_hi:[1,1,0]
	v_pk_mul_f32 v[94:95], v[44:45], v[114:115] op_sel_hi:[0,1]
	v_pk_mul_f32 v[78:79], v[112:113], v[108:109]
	v_pk_mul_f32 v[86:87], v[94:95], v[110:111]
	v_lshlrev_b32_e32 v104, 16, v45
	v_and_b32_e32 v105, 0xffff0000, v45
	s_waitcnt lgkmcnt(0)
	v_add_f32_e32 v125, v124, v125
	v_add_f32_e32 v126, v125, v126
	v_add_f32_e32 v127, v126, v127
	v_add_f32_e32 v128, v127, v128
	v_add_f32_e32 v129, v128, v129
	v_add_f32_e32 v130, v129, v130
	v_add_f32_e32 v131, v130, v131
	ds_write_b32 v155, v124 offset:0
	ds_write_b32 v155, v125 offset:256
	ds_write_b32 v155, v126 offset:512
	ds_write_b32 v155, v127 offset:768
	ds_write_b32 v155, v128 offset:1024
	ds_write_b32 v155, v129 offset:1280
	ds_write_b32 v155, v130 offset:1536
	ds_write_b32 v155, v131 offset:1792
	s_waitcnt lgkmcnt(0)
	ds_read_b128 v[116:119], v153 offset:2048
	ds_read_b128 v[120:123], v153 offset:2176
	s_waitcnt lgkmcnt(0)
	v_sub_f32_e32 v64, v64, v116
	v_exp_f32_e32 v124, v116
	v_exp_f32_e64 v116, -v116
	v_exp_f32_e32 v64, v64
	v_sub_f32_e32 v65, v65, v117
	v_exp_f32_e32 v125, v117
	v_exp_f32_e64 v117, -v117
	v_exp_f32_e32 v65, v65
	v_sub_f32_e32 v66, v66, v118
	v_exp_f32_e32 v126, v118
	v_exp_f32_e64 v118, -v118
	v_exp_f32_e32 v66, v66
	v_sub_f32_e32 v67, v67, v119
	v_exp_f32_e32 v127, v119
	v_exp_f32_e64 v119, -v119
	v_exp_f32_e32 v67, v67
	v_sub_f32_e32 v68, v68, v120
	v_exp_f32_e32 v128, v120
	v_exp_f32_e64 v120, -v120
	v_exp_f32_e32 v68, v68
	v_sub_f32_e32 v69, v69, v121
	v_exp_f32_e32 v129, v121
	v_exp_f32_e64 v121, -v121
	v_exp_f32_e32 v69, v69
	v_sub_f32_e32 v70, v70, v122
	v_exp_f32_e32 v130, v122
	v_exp_f32_e64 v122, -v122
	v_exp_f32_e32 v70, v70
	v_sub_f32_e32 v71, v71, v123
	v_exp_f32_e32 v131, v123
	v_exp_f32_e64 v123, -v123
	v_exp_f32_e32 v71, v71
	s_nop 1
	v_pk_mul_f32 v[72:73], v[72:73], v[124:125]
	v_pk_mul_f32 v[80:81], v[80:81], v[124:125]
	v_pk_mul_f32 v[88:89], v[88:89], v[64:65]
	v_pk_mul_f32 v[96:97], v[96:97], v[116:117]
	v_pk_mul_f32 v[74:75], v[74:75], v[126:127]
	v_pk_mul_f32 v[82:83], v[82:83], v[126:127]
	v_pk_mul_f32 v[90:91], v[90:91], v[66:67]
	v_pk_mul_f32 v[98:99], v[98:99], v[118:119]
	v_pk_mul_f32 v[76:77], v[76:77], v[128:129]
	v_pk_mul_f32 v[84:85], v[84:85], v[128:129]
	v_pk_mul_f32 v[92:93], v[92:93], v[68:69]
	v_pk_mul_f32 v[100:101], v[100:101], v[120:121]
	v_pk_mul_f32 v[78:79], v[78:79], v[130:131]
	v_pk_mul_f32 v[86:87], v[86:87], v[130:131]
	v_pk_mul_f32 v[94:95], v[94:95], v[70:71]
	v_pk_mul_f32 v[102:103], v[102:103], v[122:123]
	ds_write_b128 v8, v[72:75] offset:0
	ds_write_b128 v8, v[76:79] offset:128
	ds_write_b128 v8, v[80:83] offset:256
	ds_write_b128 v8, v[84:87] offset:384
	ds_write2_b32 v138, v96, v97 offset0:1 offset1:3
	ds_write2_b32 v139, v88, v89 offset0:0 offset1:2
	ds_write2_b32 v138, v98, v99 offset0:65 offset1:67
	ds_write2_b32 v139, v90, v91 offset0:64 offset1:66
	ds_write2_b32 v138, v100, v101 offset0:33 offset1:35
	ds_write2_b32 v139, v92, v93 offset0:32 offset1:34
	ds_write2_b32 v138, v102, v103 offset0:97 offset1:99
	ds_write2_b32 v139, v94, v95 offset0:96 offset1:98
	ds_write2_b32 v142, v104, v105 offset1:36
	s_and_saveexec_b64 s[68:69], s[12:13]
	ds_write_b128 v158, v[88:91] offset:0
	ds_write_b128 v158, v[92:95] offset:128
	s_mov_b64 exec, s[68:69]
	s_and_saveexec_b64 s[68:69], s[14:15]
	ds_write_b128 v159, v[116:119] offset:0
	ds_write_b128 v159, v[120:123] offset:128
	s_mov_b64 exec, s[68:69]
	global_load_dwordx2 v[28:29], v5, s[36:37]
	global_load_dwordx2 v[30:31], v5, s[36:37] offset:64
	global_load_dwordx2 v[32:33], v5, s[38:39]
	global_load_dwordx2 v[34:35], v5, s[38:39] offset:64
	global_load_dwordx2 v[36:37], v5, s[40:41]
	global_load_dwordx2 v[38:39], v5, s[40:41] offset:64
	global_load_dwordx2 v[40:41], v5, s[42:43]
	global_load_dwordx2 v[42:43], v5, s[42:43] offset:64
	global_load_dword v44, v6, s[46:47]
	global_load_dword v45, v9, s[44:45]
	v_add_u32_e32 v5, s54, v5
	v_add_u32_e32 v6, s55, v6
	v_add_u32_e32 v9, s54, v9
	s_add_i32 s6, s6, 1
	v_add_u32_e32 v146, 1, v146
	s_waitcnt lgkmcnt(0)
	ds_write_b32 v145, v146
	s_waitcnt vmcnt(10)
	v_lshlrev_b32_e32 v64, 16, v54
	v_and_b32_e32 v65, 0xffff0000, v54
	v_mul_f32_e32 v64, 0x3fb8aa3b, v64
	v_mul_f32_e32 v65, 0x3fb8aa3b, v65
	v_lshlrev_b32_e32 v66, 16, v55
	v_and_b32_e32 v67, 0xffff0000, v55
	v_mul_f32_e32 v66, 0x3fb8aa3b, v66
	v_mul_f32_e32 v67, 0x3fb8aa3b, v67
	v_lshlrev_b32_e32 v68, 16, v56
	v_and_b32_e32 v69, 0xffff0000, v56
	v_mul_f32_e32 v68, 0x3fb8aa3b, v68
	v_mul_f32_e32 v69, 0x3fb8aa3b, v69
	v_lshlrev_b32_e32 v70, 16, v57
	v_and_b32_e32 v71, 0xffff0000, v57
	v_mul_f32_e32 v70, 0x3fb8aa3b, v70
	v_mul_f32_e32 v71, 0x3fb8aa3b, v71
	ds_write_b128 v153, v[64:67]
	ds_write_b128 v153, v[68:71] offset:128
	s_waitcnt lgkmcnt(0)
	ds_read_b32 v124, v154 offset:0
	ds_read_b32 v125, v154 offset:256
	ds_read_b32 v126, v154 offset:512
	ds_read_b32 v127, v154 offset:768
	ds_read_b32 v128, v154 offset:1024
	ds_read_b32 v129, v154 offset:1280
	ds_read_b32 v130, v154 offset:1536
	ds_read_b32 v131, v154 offset:1792
	v_lshlrev_b32_e32 v108, 16, v50
	v_and_b32_e32 v109, 0xffff0000, v50
	v_lshlrev_b32_e32 v110, 16, v58
	v_and_b32_e32 v111, 0xffff0000, v58
	v_lshlrev_b32_e32 v96, 16, v46
	v_and_b32_e32 v97, 0xffff0000, v46
	v_pk_add_f32 v[112:113], v[110:111], -1.0 op_sel_hi:[1,0]
	v_pk_mul_f32 v[114:115], v[12:13], v[108:109]
	v_pk_fma_f32 v[112:113], v[20:21], v[112:113], 1.0 op_sel_hi:[1,1,0]
	v_pk_mul_f32 v[88:89], v[62:63], v[114:115] op_sel_hi:[0,1]
	v_pk_mul_f32 v[72:73], v[112:113], v[108:109]
	v_pk_mul_f32 v[80:81], v[88:89], v[110:111]
	v_lshlrev_b32_e32 v108, 16, v51
	v_and_b32_e32 v109, 0xffff0000, v51
	v_lshlrev_b32_e32 v110, 16, v59
	v_and_b32_e32 v111, 0xffff0000, v59
	v_lshlrev_b32_e32 v98, 16, v47
	v_and_b32_e32 v99, 0xffff0000, v47
	v_pk_add_f32 v[112:113], v[110:111], -1.0 op_sel_hi:[1,0]
	v_pk_mul_f32 v[114:115], v[14:15], v[108:109]
	v_pk_fma_f32 v[112:113], v[22:23], v[112:113], 1.0 op_sel_hi:[1,1,0]
	v_pk_mul_f32 v[90:91], v[62:63], v[114:115] op_sel_hi:[0,1]
	v_pk_mul_f32 v[74:75], v[112:113], v[108:109]
	v_pk_mul_f32 v[82:83], v[90:91], v[110:111]
	v_lshlrev_b32_e32 v108, 16, v52
	v_and_b32_e32 v109, 0xffff0000, v52
	v_lshlrev_b32_e32 v110, 16, v60
	v_and_b32_e32 v111, 0xffff0000, v60
	v_lshlrev_b32_e32 v100, 16, v48
	v_and_b32_e32 v101, 0xffff0000, v48
	v_pk_add_f32 v[112:113], v[110:111], -1.0 op_sel_hi:[1,0]
	v_pk_mul_f32 v[114:115], v[16:17], v[108:109]
	v_pk_fma_f32 v[112:113], v[24:25], v[112:113], 1.0 op_sel_hi:[1,1,0]
	v_pk_mul_f32 v[92:93], v[62:63], v[114:115] op_sel_hi:[0,1]
	v_pk_mul_f32 v[76:77], v[112:113], v[108:109]
	v_pk_mul_f32 v[84:85], v[92:93], v[110:111]
	v_lshlrev_b32_e32 v108, 16, v53
	v_and_b32_e32 v109, 0xffff0000, v53
	v_lshlrev_b32_e32 v110, 16, v61
	v_and_b32_e32 v111, 0xffff0000, v61
	v_lshlrev_b32_e32 v102, 16, v49
	v_and_b32_e32 v103, 0xffff0000, v49
	v_pk_add_f32 v[112:113], v[110:111], -1.0 op_sel_hi:[1,0]
	v_pk_mul_f32 v[114:115], v[18:19], v[108:109]
	v_pk_fma_f32 v[112:113], v[26:27], v[112:113], 1.0 op_sel_hi:[1,1,0]
	v_pk_mul_f32 v[94:95], v[62:63], v[114:115] op_sel_hi:[0,1]
	v_pk_mul_f32 v[78:79], v[112:113], v[108:109]
	v_pk_mul_f32 v[86:87], v[94:95], v[110:111]
	v_lshlrev_b32_e32 v104, 16, v63
	v_and_b32_e32 v105, 0xffff0000, v63
	s_waitcnt lgkmcnt(0)
	v_add_f32_e32 v125, v124, v125
	v_add_f32_e32 v126, v125, v126
	v_add_f32_e32 v127, v126, v127
	v_add_f32_e32 v128, v127, v128
	v_add_f32_e32 v129, v128, v129
	v_add_f32_e32 v130, v129, v130
	v_add_f32_e32 v131, v130, v131
	ds_write_b32 v155, v124 offset:0
	ds_write_b32 v155, v125 offset:256
	ds_write_b32 v155, v126 offset:512
	ds_write_b32 v155, v127 offset:768
	ds_write_b32 v155, v128 offset:1024
	ds_write_b32 v155, v129 offset:1280
	ds_write_b32 v155, v130 offset:1536
	ds_write_b32 v155, v131 offset:1792
	s_waitcnt lgkmcnt(0)
	ds_read_b128 v[116:119], v153 offset:2048
	ds_read_b128 v[120:123], v153 offset:2176
	s_waitcnt lgkmcnt(0)
	v_sub_f32_e32 v64, v64, v116
	v_exp_f32_e32 v124, v116
	v_exp_f32_e64 v116, -v116
	v_exp_f32_e32 v64, v64
	v_sub_f32_e32 v65, v65, v117
	v_exp_f32_e32 v125, v117
	v_exp_f32_e64 v117, -v117
	v_exp_f32_e32 v65, v65
	v_sub_f32_e32 v66, v66, v118
	v_exp_f32_e32 v126, v118
	v_exp_f32_e64 v118, -v118
	v_exp_f32_e32 v66, v66
	v_sub_f32_e32 v67, v67, v119
	v_exp_f32_e32 v127, v119
	v_exp_f32_e64 v119, -v119
	v_exp_f32_e32 v67, v67
	v_sub_f32_e32 v68, v68, v120
	v_exp_f32_e32 v128, v120
	v_exp_f32_e64 v120, -v120
	v_exp_f32_e32 v68, v68
	v_sub_f32_e32 v69, v69, v121
	v_exp_f32_e32 v129, v121
	v_exp_f32_e64 v121, -v121
	v_exp_f32_e32 v69, v69
	v_sub_f32_e32 v70, v70, v122
	v_exp_f32_e32 v130, v122
	v_exp_f32_e64 v122, -v122
	v_exp_f32_e32 v70, v70
	v_sub_f32_e32 v71, v71, v123
	v_exp_f32_e32 v131, v123
	v_exp_f32_e64 v123, -v123
	v_exp_f32_e32 v71, v71
	s_nop 1
	v_pk_mul_f32 v[72:73], v[72:73], v[124:125]
	v_pk_mul_f32 v[80:81], v[80:81], v[124:125]
	v_pk_mul_f32 v[88:89], v[88:89], v[64:65]
	v_pk_mul_f32 v[96:97], v[96:97], v[116:117]
	v_pk_mul_f32 v[74:75], v[74:75], v[126:127]
	v_pk_mul_f32 v[82:83], v[82:83], v[126:127]
	v_pk_mul_f32 v[90:91], v[90:91], v[66:67]
	v_pk_mul_f32 v[98:99], v[98:99], v[118:119]
	v_pk_mul_f32 v[76:77], v[76:77], v[128:129]
	v_pk_mul_f32 v[84:85], v[84:85], v[128:129]
	v_pk_mul_f32 v[92:93], v[92:93], v[68:69]
	v_pk_mul_f32 v[100:101], v[100:101], v[120:121]
	v_pk_mul_f32 v[78:79], v[78:79], v[130:131]
	v_pk_mul_f32 v[86:87], v[86:87], v[130:131]
	v_pk_mul_f32 v[94:95], v[94:95], v[70:71]
	v_pk_mul_f32 v[102:103], v[102:103], v[122:123]
	ds_write_b128 v8, v[72:75] offset:34816
	ds_write_b128 v8, v[76:79] offset:34944
	ds_write_b128 v8, v[80:83] offset:35072
	ds_write_b128 v8, v[84:87] offset:35200
	ds_write2_b32 v140, v96, v97 offset0:1 offset1:3
	ds_write2_b32 v141, v88, v89 offset0:0 offset1:2
	ds_write2_b32 v140, v98, v99 offset0:65 offset1:67
	ds_write2_b32 v141, v90, v91 offset0:64 offset1:66
	ds_write2_b32 v140, v100, v101 offset0:33 offset1:35
	ds_write2_b32 v141, v92, v93 offset0:32 offset1:34
	ds_write2_b32 v140, v102, v103 offset0:97 offset1:99
	ds_write2_b32 v141, v94, v95 offset0:96 offset1:98
	ds_write2_b32 v143, v104, v105 offset1:36
	s_and_saveexec_b64 s[68:69], s[12:13]
	ds_write_b128 v158, v[88:91] offset:34816
	ds_write_b128 v158, v[92:95] offset:34944
	s_mov_b64 exec, s[68:69]
	s_and_saveexec_b64 s[68:69], s[14:15]
	ds_write_b128 v159, v[116:119] offset:34816
	ds_write_b128 v159, v[120:123] offset:34944
	s_mov_b64 exec, s[68:69]
	global_load_dwordx2 v[46:47], v5, s[36:37]
	global_load_dwordx2 v[48:49], v5, s[36:37] offset:64
	global_load_dwordx2 v[50:51], v5, s[38:39]
	global_load_dwordx2 v[52:53], v5, s[38:39] offset:64
	global_load_dwordx2 v[54:55], v5, s[40:41]
	global_load_dwordx2 v[56:57], v5, s[40:41] offset:64
	global_load_dwordx2 v[58:59], v5, s[42:43]
	global_load_dwordx2 v[60:61], v5, s[42:43] offset:64
	global_load_dword v62, v6, s[46:47]
	global_load_dword v63, v9, s[44:45]
	v_add_u32_e32 v5, s54, v5
	v_add_u32_e32 v6, s55, v6
	v_add_u32_e32 v9, s54, v9
	s_add_i32 s6, s6, 1
	v_add_u32_e32 v146, 1, v146
	s_waitcnt lgkmcnt(0)
	ds_write_b32 v145, v146
.Lsc_G_loop:
	s_sub_u32 s65, s6, 1
	s_mov_b32 s69, 0x100000

.Lsc_G_gom0:
	s_waitcnt vmcnt(10)
	v_lshlrev_b32_e32 v64, 16, v36
	v_and_b32_e32 v65, 0xffff0000, v36
	v_mul_f32_e32 v64, 0x3fb8aa3b, v64
	v_mul_f32_e32 v65, 0x3fb8aa3b, v65
	v_lshlrev_b32_e32 v66, 16, v37
	v_and_b32_e32 v67, 0xffff0000, v37
	v_mul_f32_e32 v66, 0x3fb8aa3b, v66
	v_mul_f32_e32 v67, 0x3fb8aa3b, v67
	v_lshlrev_b32_e32 v68, 16, v38
	v_and_b32_e32 v69, 0xffff0000, v38
	v_mul_f32_e32 v68, 0x3fb8aa3b, v68
	v_mul_f32_e32 v69, 0x3fb8aa3b, v69
	v_lshlrev_b32_e32 v70, 16, v39
	v_and_b32_e32 v71, 0xffff0000, v39
	v_mul_f32_e32 v70, 0x3fb8aa3b, v70
	v_mul_f32_e32 v71, 0x3fb8aa3b, v71
	ds_write_b128 v153, v[64:67]
	ds_write_b128 v153, v[68:71] offset:128
	s_waitcnt lgkmcnt(0)
	ds_read_b32 v124, v154 offset:0
	ds_read_b32 v125, v154 offset:256
	ds_read_b32 v126, v154 offset:512
	ds_read_b32 v127, v154 offset:768
	ds_read_b32 v128, v154 offset:1024
	ds_read_b32 v129, v154 offset:1280
	ds_read_b32 v130, v154 offset:1536
	ds_read_b32 v131, v154 offset:1792
	v_lshlrev_b32_e32 v108, 16, v32
	v_and_b32_e32 v109, 0xffff0000, v32
	v_lshlrev_b32_e32 v110, 16, v40
	v_and_b32_e32 v111, 0xffff0000, v40
	v_lshlrev_b32_e32 v96, 16, v28
	v_and_b32_e32 v97, 0xffff0000, v28
	v_pk_add_f32 v[112:113], v[110:111], -1.0 op_sel_hi:[1,0]
	v_pk_mul_f32 v[114:115], v[12:13], v[108:109]
	v_pk_fma_f32 v[112:113], v[20:21], v[112:113], 1.0 op_sel_hi:[1,1,0]
	v_pk_mul_f32 v[88:89], v[44:45], v[114:115] op_sel_hi:[0,1]
	v_pk_mul_f32 v[72:73], v[112:113], v[108:109]
	v_pk_mul_f32 v[80:81], v[88:89], v[110:111]
	v_lshlrev_b32_e32 v108, 16, v33
	v_and_b32_e32 v109, 0xffff0000, v33
	v_lshlrev_b32_e32 v110, 16, v41
	v_and_b32_e32 v111, 0xffff0000, v41
	v_lshlrev_b32_e32 v98, 16, v29
	v_and_b32_e32 v99, 0xffff0000, v29
	v_pk_add_f32 v[112:113], v[110:111], -1.0 op_sel_hi:[1,0]
	v_pk_mul_f32 v[114:115], v[14:15], v[108:109]
	v_pk_fma_f32 v[112:113], v[22:23], v[112:113], 1.0 op_sel_hi:[1,1,0]
	v_pk_mul_f32 v[90:91], v[44:45], v[114:115] op_sel_hi:[0,1]
	v_pk_mul_f32 v[74:75], v[112:113], v[108:109]
	v_pk_mul_f32 v[82:83], v[90:91], v[110:111]
	v_lshlrev_b32_e32 v108, 16, v34
	v_and_b32_e32 v109, 0xffff0000, v34
	v_lshlrev_b32_e32 v110, 16, v42
	v_and_b32_e32 v111, 0xffff0000, v42
	v_lshlrev_b32_e32 v100, 16, v30
	v_and_b32_e32 v101, 0xffff0000, v30
	v_pk_add_f32 v[112:113], v[110:111], -1.0 op_sel_hi:[1,0]
	v_pk_mul_f32 v[114:115], v[16:17], v[108:109]
	v_pk_fma_f32 v[112:113], v[24:25], v[112:113], 1.0 op_sel_hi:[1,1,0]
	v_pk_mul_f32 v[92:93], v[44:45], v[114:115] op_sel_hi:[0,1]
	v_pk_mul_f32 v[76:77], v[112:113], v[108:109]
	v_pk_mul_f32 v[84:85], v[92:93], v[110:111]
	v_lshlrev_b32_e32 v108, 16, v35
	v_and_b32_e32 v109, 0xffff0000, v35
	v_lshlrev_b32_e32 v110, 16, v43
	v_and_b32_e32 v111, 0xffff0000, v43
	v_lshlrev_b32_e32 v102, 16, v31
	v_and_b32_e32 v103, 0xffff0000, v31
	v_pk_add_f32 v[112:113], v[110:111], -1.0 op_sel_hi:[1,0]
	v_pk_mul_f32 v[114:115], v[18:19], v[108:109]
	v_pk_fma_f32 v[112:113], v[26:27], v[112:113], 1.0 op_sel_hi:[1,1,0]
	v_pk_mul_f32 v[94:95], v[44:45], v[114:115] op_sel_hi:[0,1]
	v_pk_mul_f32 v[78:79], v[112:113], v[108:109]
	v_pk_mul_f32 v[86:87], v[94:95], v[110:111]
	v_lshlrev_b32_e32 v104, 16, v45
	v_and_b32_e32 v105, 0xffff0000, v45
	s_waitcnt lgkmcnt(0)
	v_add_f32_e32 v125, v124, v125
	v_add_f32_e32 v126, v125, v126
	v_add_f32_e32 v127, v126, v127
	v_add_f32_e32 v128, v127, v128
	v_add_f32_e32 v129, v128, v129
	v_add_f32_e32 v130, v129, v130
	v_add_f32_e32 v131, v130, v131
	ds_write_b32 v155, v124 offset:0
	ds_write_b32 v155, v125 offset:256
	ds_write_b32 v155, v126 offset:512
	ds_write_b32 v155, v127 offset:768
	ds_write_b32 v155, v128 offset:1024
	ds_write_b32 v155, v129 offset:1280
	ds_write_b32 v155, v130 offset:1536
	ds_write_b32 v155, v131 offset:1792
	s_waitcnt lgkmcnt(0)
	ds_read_b128 v[116:119], v153 offset:2048
	ds_read_b128 v[120:123], v153 offset:2176
	s_waitcnt lgkmcnt(0)
	v_sub_f32_e32 v64, v64, v116
	v_exp_f32_e32 v124, v116
	v_exp_f32_e64 v116, -v116
	v_exp_f32_e32 v64, v64
	v_sub_f32_e32 v65, v65, v117
	v_exp_f32_e32 v125, v117
	v_exp_f32_e64 v117, -v117
	v_exp_f32_e32 v65, v65
	v_sub_f32_e32 v66, v66, v118
	v_exp_f32_e32 v126, v118
	v_exp_f32_e64 v118, -v118
	v_exp_f32_e32 v66, v66
	v_sub_f32_e32 v67, v67, v119
	v_exp_f32_e32 v127, v119
	v_exp_f32_e64 v119, -v119
	v_exp_f32_e32 v67, v67
	v_sub_f32_e32 v68, v68, v120
	v_exp_f32_e32 v128, v120
	v_exp_f32_e64 v120, -v120
	v_exp_f32_e32 v68, v68
	v_sub_f32_e32 v69, v69, v121
	v_exp_f32_e32 v129, v121
	v_exp_f32_e64 v121, -v121
	v_exp_f32_e32 v69, v69
	v_sub_f32_e32 v70, v70, v122
	v_exp_f32_e32 v130, v122
	v_exp_f32_e64 v122, -v122
	v_exp_f32_e32 v70, v70
	v_sub_f32_e32 v71, v71, v123
	v_exp_f32_e32 v131, v123
	v_exp_f32_e64 v123, -v123
	v_exp_f32_e32 v71, v71
	s_nop 1
	v_pk_mul_f32 v[72:73], v[72:73], v[124:125]
	v_pk_mul_f32 v[80:81], v[80:81], v[124:125]
	v_pk_mul_f32 v[88:89], v[88:89], v[64:65]
	v_pk_mul_f32 v[96:97], v[96:97], v[116:117]
	v_pk_mul_f32 v[74:75], v[74:75], v[126:127]
	v_pk_mul_f32 v[82:83], v[82:83], v[126:127]
	v_pk_mul_f32 v[90:91], v[90:91], v[66:67]
	v_pk_mul_f32 v[98:99], v[98:99], v[118:119]
	v_pk_mul_f32 v[76:77], v[76:77], v[128:129]
	v_pk_mul_f32 v[84:85], v[84:85], v[128:129]
	v_pk_mul_f32 v[92:93], v[92:93], v[68:69]
	v_pk_mul_f32 v[100:101], v[100:101], v[120:121]
	v_pk_mul_f32 v[78:79], v[78:79], v[130:131]
	v_pk_mul_f32 v[86:87], v[86:87], v[130:131]
	v_pk_mul_f32 v[94:95], v[94:95], v[70:71]
	v_pk_mul_f32 v[102:103], v[102:103], v[122:123]
	ds_write_b128 v8, v[72:75] offset:0
	ds_write_b128 v8, v[76:79] offset:128
	ds_write_b128 v8, v[80:83] offset:256
	ds_write_b128 v8, v[84:87] offset:384
	ds_write2_b32 v138, v96, v97 offset0:1 offset1:3
	ds_write2_b32 v139, v88, v89 offset0:0 offset1:2
	ds_write2_b32 v138, v98, v99 offset0:65 offset1:67
	ds_write2_b32 v139, v90, v91 offset0:64 offset1:66
	ds_write2_b32 v138, v100, v101 offset0:33 offset1:35
	ds_write2_b32 v139, v92, v93 offset0:32 offset1:34
	ds_write2_b32 v138, v102, v103 offset0:97 offset1:99
	ds_write2_b32 v139, v94, v95 offset0:96 offset1:98
	ds_write2_b32 v142, v104, v105 offset1:36
	s_and_saveexec_b64 s[68:69], s[12:13]
	ds_write_b128 v158, v[88:91] offset:0
	ds_write_b128 v158, v[92:95] offset:128
	s_mov_b64 exec, s[68:69]
	s_and_saveexec_b64 s[68:69], s[14:15]
	ds_write_b128 v159, v[116:119] offset:0
	ds_write_b128 v159, v[120:123] offset:128
	s_mov_b64 exec, s[68:69]
	global_load_dwordx2 v[28:29], v5, s[36:37]
	global_load_dwordx2 v[30:31], v5, s[36:37] offset:64
	global_load_dwordx2 v[32:33], v5, s[38:39]
	global_load_dwordx2 v[34:35], v5, s[38:39] offset:64
	global_load_dwordx2 v[36:37], v5, s[40:41]
	global_load_dwordx2 v[38:39], v5, s[40:41] offset:64
	global_load_dwordx2 v[40:41], v5, s[42:43]
	global_load_dwordx2 v[42:43], v5, s[42:43] offset:64
	global_load_dword v44, v6, s[46:47]
	global_load_dword v45, v9, s[44:45]
	v_add_u32_e32 v5, s54, v5
	v_add_u32_e32 v6, s55, v6
	v_add_u32_e32 v9, s54, v9
	ds_read_b128 v[120:123], v11 offset:0
	ds_read_b128 v[124:127], v11 offset:16
	ds_read_b128 v[128:131], v11 offset:32
	ds_read_b128 v[132:135], v11 offset:48
	s_waitcnt lgkmcnt(0)
	v_add_f32_e32 v120, v120, v121
	v_add_f32_e32 v122, v122, v123
	v_add_f32_e32 v124, v124, v125
	v_add_f32_e32 v126, v126, v127
	v_add_f32_e32 v120, v120, v122
	v_add_f32_e32 v124, v124, v126
	v_add_f32_e32 v136, v120, v124
	v_add_f32_e32 v128, v128, v129
	v_add_f32_e32 v130, v130, v131
	v_add_f32_e32 v132, v132, v133
	v_add_f32_e32 v134, v134, v135
	v_add_f32_e32 v128, v128, v130
	v_add_f32_e32 v132, v132, v134
	v_add_f32_e32 v137, v128, v132
	global_store_dwordx2 v7, v[136:137], s[48:49]
	v_add_u32_e32 v7, s64, v7
	s_add_i32 s6, s6, 1
	v_add_u32_e32 v146, 1, v146
	s_waitcnt lgkmcnt(0)
	ds_write_b32 v145, v146
	s_sub_u32 s65, s6, 1
	s_mov_b32 s69, 0x100000

.Lsc_G_gom1:
	s_waitcnt vmcnt(10)
	v_lshlrev_b32_e32 v64, 16, v54
	v_and_b32_e32 v65, 0xffff0000, v54
	v_mul_f32_e32 v64, 0x3fb8aa3b, v64
	v_mul_f32_e32 v65, 0x3fb8aa3b, v65
	v_lshlrev_b32_e32 v66, 16, v55
	v_and_b32_e32 v67, 0xffff0000, v55
	v_mul_f32_e32 v66, 0x3fb8aa3b, v66
	v_mul_f32_e32 v67, 0x3fb8aa3b, v67
	v_lshlrev_b32_e32 v68, 16, v56
	v_and_b32_e32 v69, 0xffff0000, v56
	v_mul_f32_e32 v68, 0x3fb8aa3b, v68
	v_mul_f32_e32 v69, 0x3fb8aa3b, v69
	v_lshlrev_b32_e32 v70, 16, v57
	v_and_b32_e32 v71, 0xffff0000, v57
	v_mul_f32_e32 v70, 0x3fb8aa3b, v70
	v_mul_f32_e32 v71, 0x3fb8aa3b, v71
	ds_write_b128 v153, v[64:67]
	ds_write_b128 v153, v[68:71] offset:128
	s_waitcnt lgkmcnt(0)
	ds_read_b32 v124, v154 offset:0
	ds_read_b32 v125, v154 offset:256
	ds_read_b32 v126, v154 offset:512
	ds_read_b32 v127, v154 offset:768
	ds_read_b32 v128, v154 offset:1024
	ds_read_b32 v129, v154 offset:1280
	ds_read_b32 v130, v154 offset:1536
	ds_read_b32 v131, v154 offset:1792
	v_lshlrev_b32_e32 v108, 16, v50
	v_and_b32_e32 v109, 0xffff0000, v50
	v_lshlrev_b32_e32 v110, 16, v58
	v_and_b32_e32 v111, 0xffff0000, v58
	v_lshlrev_b32_e32 v96, 16, v46
	v_and_b32_e32 v97, 0xffff0000, v46
	v_pk_add_f32 v[112:113], v[110:111], -1.0 op_sel_hi:[1,0]
	v_pk_mul_f32 v[114:115], v[12:13], v[108:109]
	v_pk_fma_f32 v[112:113], v[20:21], v[112:113], 1.0 op_sel_hi:[1,1,0]
	v_pk_mul_f32 v[88:89], v[62:63], v[114:115] op_sel_hi:[0,1]
	v_pk_mul_f32 v[72:73], v[112:113], v[108:109]
	v_pk_mul_f32 v[80:81], v[88:89], v[110:111]
	v_lshlrev_b32_e32 v108, 16, v51
	v_and_b32_e32 v109, 0xffff0000, v51
	v_lshlrev_b32_e32 v110, 16, v59
	v_and_b32_e32 v111, 0xffff0000, v59
	v_lshlrev_b32_e32 v98, 16, v47
	v_and_b32_e32 v99, 0xffff0000, v47
	v_pk_add_f32 v[112:113], v[110:111], -1.0 op_sel_hi:[1,0]
	v_pk_mul_f32 v[114:115], v[14:15], v[108:109]
	v_pk_fma_f32 v[112:113], v[22:23], v[112:113], 1.0 op_sel_hi:[1,1,0]
	v_pk_mul_f32 v[90:91], v[62:63], v[114:115] op_sel_hi:[0,1]
	v_pk_mul_f32 v[74:75], v[112:113], v[108:109]
	v_pk_mul_f32 v[82:83], v[90:91], v[110:111]
	v_lshlrev_b32_e32 v108, 16, v52
	v_and_b32_e32 v109, 0xffff0000, v52
	v_lshlrev_b32_e32 v110, 16, v60
	v_and_b32_e32 v111, 0xffff0000, v60
	v_lshlrev_b32_e32 v100, 16, v48
	v_and_b32_e32 v101, 0xffff0000, v48
	v_pk_add_f32 v[112:113], v[110:111], -1.0 op_sel_hi:[1,0]
	v_pk_mul_f32 v[114:115], v[16:17], v[108:109]
	v_pk_fma_f32 v[112:113], v[24:25], v[112:113], 1.0 op_sel_hi:[1,1,0]
	v_pk_mul_f32 v[92:93], v[62:63], v[114:115] op_sel_hi:[0,1]
	v_pk_mul_f32 v[76:77], v[112:113], v[108:109]
	v_pk_mul_f32 v[84:85], v[92:93], v[110:111]
	v_lshlrev_b32_e32 v108, 16, v53
	v_and_b32_e32 v109, 0xffff0000, v53
	v_lshlrev_b32_e32 v110, 16, v61
	v_and_b32_e32 v111, 0xffff0000, v61
	v_lshlrev_b32_e32 v102, 16, v49
	v_and_b32_e32 v103, 0xffff0000, v49
	v_pk_add_f32 v[112:113], v[110:111], -1.0 op_sel_hi:[1,0]
	v_pk_mul_f32 v[114:115], v[18:19], v[108:109]
	v_pk_fma_f32 v[112:113], v[26:27], v[112:113], 1.0 op_sel_hi:[1,1,0]
	v_pk_mul_f32 v[94:95], v[62:63], v[114:115] op_sel_hi:[0,1]
	v_pk_mul_f32 v[78:79], v[112:113], v[108:109]
	v_pk_mul_f32 v[86:87], v[94:95], v[110:111]
	v_lshlrev_b32_e32 v104, 16, v63
	v_and_b32_e32 v105, 0xffff0000, v63
	s_waitcnt lgkmcnt(0)
	v_add_f32_e32 v125, v124, v125
	v_add_f32_e32 v126, v125, v126
	v_add_f32_e32 v127, v126, v127
	v_add_f32_e32 v128, v127, v128
	v_add_f32_e32 v129, v128, v129
	v_add_f32_e32 v130, v129, v130
	v_add_f32_e32 v131, v130, v131
	ds_write_b32 v155, v124 offset:0
	ds_write_b32 v155, v125 offset:256
	ds_write_b32 v155, v126 offset:512
	ds_write_b32 v155, v127 offset:768
	ds_write_b32 v155, v128 offset:1024
	ds_write_b32 v155, v129 offset:1280
	ds_write_b32 v155, v130 offset:1536
	ds_write_b32 v155, v131 offset:1792
	s_waitcnt lgkmcnt(0)
	ds_read_b128 v[116:119], v153 offset:2048
	ds_read_b128 v[120:123], v153 offset:2176
	s_waitcnt lgkmcnt(0)
	v_sub_f32_e32 v64, v64, v116
	v_exp_f32_e32 v124, v116
	v_exp_f32_e64 v116, -v116
	v_exp_f32_e32 v64, v64
	v_sub_f32_e32 v65, v65, v117
	v_exp_f32_e32 v125, v117
	v_exp_f32_e64 v117, -v117
	v_exp_f32_e32 v65, v65
	v_sub_f32_e32 v66, v66, v118
	v_exp_f32_e32 v126, v118
	v_exp_f32_e64 v118, -v118
	v_exp_f32_e32 v66, v66
	v_sub_f32_e32 v67, v67, v119
	v_exp_f32_e32 v127, v119
	v_exp_f32_e64 v119, -v119
	v_exp_f32_e32 v67, v67
	v_sub_f32_e32 v68, v68, v120
	v_exp_f32_e32 v128, v120
	v_exp_f32_e64 v120, -v120
	v_exp_f32_e32 v68, v68
	v_sub_f32_e32 v69, v69, v121
	v_exp_f32_e32 v129, v121
	v_exp_f32_e64 v121, -v121
	v_exp_f32_e32 v69, v69
	v_sub_f32_e32 v70, v70, v122
	v_exp_f32_e32 v130, v122
	v_exp_f32_e64 v122, -v122
	v_exp_f32_e32 v70, v70
	v_sub_f32_e32 v71, v71, v123
	v_exp_f32_e32 v131, v123
	v_exp_f32_e64 v123, -v123
	v_exp_f32_e32 v71, v71
	s_nop 1
	v_pk_mul_f32 v[72:73], v[72:73], v[124:125]
	v_pk_mul_f32 v[80:81], v[80:81], v[124:125]
	v_pk_mul_f32 v[88:89], v[88:89], v[64:65]
	v_pk_mul_f32 v[96:97], v[96:97], v[116:117]
	v_pk_mul_f32 v[74:75], v[74:75], v[126:127]
	v_pk_mul_f32 v[82:83], v[82:83], v[126:127]
	v_pk_mul_f32 v[90:91], v[90:91], v[66:67]
	v_pk_mul_f32 v[98:99], v[98:99], v[118:119]
	v_pk_mul_f32 v[76:77], v[76:77], v[128:129]
	v_pk_mul_f32 v[84:85], v[84:85], v[128:129]
	v_pk_mul_f32 v[92:93], v[92:93], v[68:69]
	v_pk_mul_f32 v[100:101], v[100:101], v[120:121]
	v_pk_mul_f32 v[78:79], v[78:79], v[130:131]
	v_pk_mul_f32 v[86:87], v[86:87], v[130:131]
	v_pk_mul_f32 v[94:95], v[94:95], v[70:71]
	v_pk_mul_f32 v[102:103], v[102:103], v[122:123]
	ds_write_b128 v8, v[72:75] offset:34816
	ds_write_b128 v8, v[76:79] offset:34944
	ds_write_b128 v8, v[80:83] offset:35072
	ds_write_b128 v8, v[84:87] offset:35200
	ds_write2_b32 v140, v96, v97 offset0:1 offset1:3
	ds_write2_b32 v141, v88, v89 offset0:0 offset1:2
	ds_write2_b32 v140, v98, v99 offset0:65 offset1:67
	ds_write2_b32 v141, v90, v91 offset0:64 offset1:66
	ds_write2_b32 v140, v100, v101 offset0:33 offset1:35
	ds_write2_b32 v141, v92, v93 offset0:32 offset1:34
	ds_write2_b32 v140, v102, v103 offset0:97 offset1:99
	ds_write2_b32 v141, v94, v95 offset0:96 offset1:98
	ds_write2_b32 v143, v104, v105 offset1:36
	s_and_saveexec_b64 s[68:69], s[12:13]
	ds_write_b128 v158, v[88:91] offset:34816
	ds_write_b128 v158, v[92:95] offset:34944
	s_mov_b64 exec, s[68:69]
	s_and_saveexec_b64 s[68:69], s[14:15]
	ds_write_b128 v159, v[116:119] offset:34816
	ds_write_b128 v159, v[120:123] offset:34944
	s_mov_b64 exec, s[68:69]
	global_load_dwordx2 v[46:47], v5, s[36:37]
	global_load_dwordx2 v[48:49], v5, s[36:37] offset:64
	global_load_dwordx2 v[50:51], v5, s[38:39]
	global_load_dwordx2 v[52:53], v5, s[38:39] offset:64
	global_load_dwordx2 v[54:55], v5, s[40:41]
	global_load_dwordx2 v[56:57], v5, s[40:41] offset:64
	global_load_dwordx2 v[58:59], v5, s[42:43]
	global_load_dwordx2 v[60:61], v5, s[42:43] offset:64
	global_load_dword v62, v6, s[46:47]
	global_load_dword v63, v9, s[44:45]
	v_add_u32_e32 v5, s54, v5
	v_add_u32_e32 v6, s55, v6
	v_add_u32_e32 v9, s54, v9
	ds_read_b128 v[120:123], v11 offset:16384
	ds_read_b128 v[124:127], v11 offset:16400
	ds_read_b128 v[128:131], v11 offset:16416
	ds_read_b128 v[132:135], v11 offset:16432
	s_waitcnt lgkmcnt(0)
	v_add_f32_e32 v120, v120, v121
	v_add_f32_e32 v122, v122, v123
	v_add_f32_e32 v124, v124, v125
	v_add_f32_e32 v126, v126, v127
	v_add_f32_e32 v120, v120, v122
	v_add_f32_e32 v124, v124, v126
	v_add_f32_e32 v136, v120, v124
	v_add_f32_e32 v128, v128, v129
	v_add_f32_e32 v130, v130, v131
	v_add_f32_e32 v132, v132, v133
	v_add_f32_e32 v134, v134, v135
	v_add_f32_e32 v128, v128, v130
	v_add_f32_e32 v132, v132, v134
	v_add_f32_e32 v137, v128, v132
	global_store_dwordx2 v7, v[136:137], s[48:49]
	v_add_u32_e32 v7, s64, v7
	s_add_i32 s6, s6, 1
	v_add_u32_e32 v146, 1, v146
	s_waitcnt lgkmcnt(0)
	ds_write_b32 v145, v146
	s_cmp_lt_u32 s6, 0xfe
	s_cbranch_scc1 .Lsc_G_loop
	s_sub_u32 s65, s6, 1
	s_mov_b32 s69, 0x100000

.Lsc_G_goz0:
	s_waitcnt vmcnt(10)
	v_lshlrev_b32_e32 v64, 16, v36
	v_and_b32_e32 v65, 0xffff0000, v36
	v_mul_f32_e32 v64, 0x3fb8aa3b, v64
	v_mul_f32_e32 v65, 0x3fb8aa3b, v65
	v_lshlrev_b32_e32 v66, 16, v37
	v_and_b32_e32 v67, 0xffff0000, v37
	v_mul_f32_e32 v66, 0x3fb8aa3b, v66
	v_mul_f32_e32 v67, 0x3fb8aa3b, v67
	v_lshlrev_b32_e32 v68, 16, v38
	v_and_b32_e32 v69, 0xffff0000, v38
	v_mul_f32_e32 v68, 0x3fb8aa3b, v68
	v_mul_f32_e32 v69, 0x3fb8aa3b, v69
	v_lshlrev_b32_e32 v70, 16, v39
	v_and_b32_e32 v71, 0xffff0000, v39
	v_mul_f32_e32 v70, 0x3fb8aa3b, v70
	v_mul_f32_e32 v71, 0x3fb8aa3b, v71
	ds_write_b128 v153, v[64:67]
	ds_write_b128 v153, v[68:71] offset:128
	s_waitcnt lgkmcnt(0)
	ds_read_b32 v124, v154 offset:0
	ds_read_b32 v125, v154 offset:256
	ds_read_b32 v126, v154 offset:512
	ds_read_b32 v127, v154 offset:768
	ds_read_b32 v128, v154 offset:1024
	ds_read_b32 v129, v154 offset:1280
	ds_read_b32 v130, v154 offset:1536
	ds_read_b32 v131, v154 offset:1792
	v_lshlrev_b32_e32 v108, 16, v32
	v_and_b32_e32 v109, 0xffff0000, v32
	v_lshlrev_b32_e32 v110, 16, v40
	v_and_b32_e32 v111, 0xffff0000, v40
	v_lshlrev_b32_e32 v96, 16, v28
	v_and_b32_e32 v97, 0xffff0000, v28
	v_pk_add_f32 v[112:113], v[110:111], -1.0 op_sel_hi:[1,0]
	v_pk_mul_f32 v[114:115], v[12:13], v[108:109]
	v_pk_fma_f32 v[112:113], v[20:21], v[112:113], 1.0 op_sel_hi:[1,1,0]
	v_pk_mul_f32 v[88:89], v[44:45], v[114:115] op_sel_hi:[0,1]
	v_pk_mul_f32 v[72:73], v[112:113], v[108:109]
	v_pk_mul_f32 v[80:81], v[88:89], v[110:111]
	v_lshlrev_b32_e32 v108, 16, v33
	v_and_b32_e32 v109, 0xffff0000, v33
	v_lshlrev_b32_e32 v110, 16, v41
	v_and_b32_e32 v111, 0xffff0000, v41
	v_lshlrev_b32_e32 v98, 16, v29
	v_and_b32_e32 v99, 0xffff0000, v29
	v_pk_add_f32 v[112:113], v[110:111], -1.0 op_sel_hi:[1,0]
	v_pk_mul_f32 v[114:115], v[14:15], v[108:109]
	v_pk_fma_f32 v[112:113], v[22:23], v[112:113], 1.0 op_sel_hi:[1,1,0]
	v_pk_mul_f32 v[90:91], v[44:45], v[114:115] op_sel_hi:[0,1]
	v_pk_mul_f32 v[74:75], v[112:113], v[108:109]
	v_pk_mul_f32 v[82:83], v[90:91], v[110:111]
	v_lshlrev_b32_e32 v108, 16, v34
	v_and_b32_e32 v109, 0xffff0000, v34
	v_lshlrev_b32_e32 v110, 16, v42
	v_and_b32_e32 v111, 0xffff0000, v42
	v_lshlrev_b32_e32 v100, 16, v30
	v_and_b32_e32 v101, 0xffff0000, v30
	v_pk_add_f32 v[112:113], v[110:111], -1.0 op_sel_hi:[1,0]
	v_pk_mul_f32 v[114:115], v[16:17], v[108:109]
	v_pk_fma_f32 v[112:113], v[24:25], v[112:113], 1.0 op_sel_hi:[1,1,0]
	v_pk_mul_f32 v[92:93], v[44:45], v[114:115] op_sel_hi:[0,1]
	v_pk_mul_f32 v[76:77], v[112:113], v[108:109]
	v_pk_mul_f32 v[84:85], v[92:93], v[110:111]
	v_lshlrev_b32_e32 v108, 16, v35
	v_and_b32_e32 v109, 0xffff0000, v35
	v_lshlrev_b32_e32 v110, 16, v43
	v_and_b32_e32 v111, 0xffff0000, v43
	v_lshlrev_b32_e32 v102, 16, v31
	v_and_b32_e32 v103, 0xffff0000, v31
	v_pk_add_f32 v[112:113], v[110:111], -1.0 op_sel_hi:[1,0]
	v_pk_mul_f32 v[114:115], v[18:19], v[108:109]
	v_pk_fma_f32 v[112:113], v[26:27], v[112:113], 1.0 op_sel_hi:[1,1,0]
	v_pk_mul_f32 v[94:95], v[44:45], v[114:115] op_sel_hi:[0,1]
	v_pk_mul_f32 v[78:79], v[112:113], v[108:109]
	v_pk_mul_f32 v[86:87], v[94:95], v[110:111]
	v_lshlrev_b32_e32 v104, 16, v45
	v_and_b32_e32 v105, 0xffff0000, v45
	s_waitcnt lgkmcnt(0)
	v_add_f32_e32 v125, v124, v125
	v_add_f32_e32 v126, v125, v126
	v_add_f32_e32 v127, v126, v127
	v_add_f32_e32 v128, v127, v128
	v_add_f32_e32 v129, v128, v129
	v_add_f32_e32 v130, v129, v130
	v_add_f32_e32 v131, v130, v131
	ds_write_b32 v155, v124 offset:0
	ds_write_b32 v155, v125 offset:256
	ds_write_b32 v155, v126 offset:512
	ds_write_b32 v155, v127 offset:768
	ds_write_b32 v155, v128 offset:1024
	ds_write_b32 v155, v129 offset:1280
	ds_write_b32 v155, v130 offset:1536
	ds_write_b32 v155, v131 offset:1792
	s_waitcnt lgkmcnt(0)
	ds_read_b128 v[116:119], v153 offset:2048
	ds_read_b128 v[120:123], v153 offset:2176
	s_waitcnt lgkmcnt(0)
	v_sub_f32_e32 v64, v64, v116
	v_exp_f32_e32 v124, v116
	v_exp_f32_e64 v116, -v116
	v_exp_f32_e32 v64, v64
	v_sub_f32_e32 v65, v65, v117
	v_exp_f32_e32 v125, v117
	v_exp_f32_e64 v117, -v117
	v_exp_f32_e32 v65, v65
	v_sub_f32_e32 v66, v66, v118
	v_exp_f32_e32 v126, v118
	v_exp_f32_e64 v118, -v118
	v_exp_f32_e32 v66, v66
	v_sub_f32_e32 v67, v67, v119
	v_exp_f32_e32 v127, v119
	v_exp_f32_e64 v119, -v119
	v_exp_f32_e32 v67, v67
	v_sub_f32_e32 v68, v68, v120
	v_exp_f32_e32 v128, v120
	v_exp_f32_e64 v120, -v120
	v_exp_f32_e32 v68, v68
	v_sub_f32_e32 v69, v69, v121
	v_exp_f32_e32 v129, v121
	v_exp_f32_e64 v121, -v121
	v_exp_f32_e32 v69, v69
	v_sub_f32_e32 v70, v70, v122
	v_exp_f32_e32 v130, v122
	v_exp_f32_e64 v122, -v122
	v_exp_f32_e32 v70, v70
	v_sub_f32_e32 v71, v71, v123
	v_exp_f32_e32 v131, v123
	v_exp_f32_e64 v123, -v123
	v_exp_f32_e32 v71, v71
	s_nop 1
	v_pk_mul_f32 v[72:73], v[72:73], v[124:125]
	v_pk_mul_f32 v[80:81], v[80:81], v[124:125]
	v_pk_mul_f32 v[88:89], v[88:89], v[64:65]
	v_pk_mul_f32 v[96:97], v[96:97], v[116:117]
	v_pk_mul_f32 v[74:75], v[74:75], v[126:127]
	v_pk_mul_f32 v[82:83], v[82:83], v[126:127]
	v_pk_mul_f32 v[90:91], v[90:91], v[66:67]
	v_pk_mul_f32 v[98:99], v[98:99], v[118:119]
	v_pk_mul_f32 v[76:77], v[76:77], v[128:129]
	v_pk_mul_f32 v[84:85], v[84:85], v[128:129]
	v_pk_mul_f32 v[92:93], v[92:93], v[68:69]
	v_pk_mul_f32 v[100:101], v[100:101], v[120:121]
	v_pk_mul_f32 v[78:79], v[78:79], v[130:131]
	v_pk_mul_f32 v[86:87], v[86:87], v[130:131]
	v_pk_mul_f32 v[94:95], v[94:95], v[70:71]
	v_pk_mul_f32 v[102:103], v[102:103], v[122:123]
	ds_write_b128 v8, v[72:75] offset:0
	ds_write_b128 v8, v[76:79] offset:128
	ds_write_b128 v8, v[80:83] offset:256
	ds_write_b128 v8, v[84:87] offset:384
	ds_write2_b32 v138, v96, v97 offset0:1 offset1:3
	ds_write2_b32 v139, v88, v89 offset0:0 offset1:2
	ds_write2_b32 v138, v98, v99 offset0:65 offset1:67
	ds_write2_b32 v139, v90, v91 offset0:64 offset1:66
	ds_write2_b32 v138, v100, v101 offset0:33 offset1:35
	ds_write2_b32 v139, v92, v93 offset0:32 offset1:34
	ds_write2_b32 v138, v102, v103 offset0:97 offset1:99
	ds_write2_b32 v139, v94, v95 offset0:96 offset1:98
	ds_write2_b32 v142, v104, v105 offset1:36
	s_and_saveexec_b64 s[68:69], s[12:13]
	ds_write_b128 v158, v[88:91] offset:0
	ds_write_b128 v158, v[92:95] offset:128
	s_mov_b64 exec, s[68:69]
	s_and_saveexec_b64 s[68:69], s[14:15]
	ds_write_b128 v159, v[116:119] offset:0
	ds_write_b128 v159, v[120:123] offset:128
	s_mov_b64 exec, s[68:69]
	ds_read_b128 v[120:123], v11 offset:0
	ds_read_b128 v[124:127], v11 offset:16
	ds_read_b128 v[128:131], v11 offset:32
	ds_read_b128 v[132:135], v11 offset:48
	s_waitcnt lgkmcnt(0)
	v_add_f32_e32 v120, v120, v121
	v_add_f32_e32 v122, v122, v123
	v_add_f32_e32 v124, v124, v125
	v_add_f32_e32 v126, v126, v127
	v_add_f32_e32 v120, v120, v122
	v_add_f32_e32 v124, v124, v126
	v_add_f32_e32 v136, v120, v124
	v_add_f32_e32 v128, v128, v129
	v_add_f32_e32 v130, v130, v131
	v_add_f32_e32 v132, v132, v133
	v_add_f32_e32 v134, v134, v135
	v_add_f32_e32 v128, v128, v130
	v_add_f32_e32 v132, v132, v134
	v_add_f32_e32 v137, v128, v132
	global_store_dwordx2 v7, v[136:137], s[48:49]
	v_add_u32_e32 v7, s64, v7
	s_add_i32 s6, s6, 1
	v_add_u32_e32 v146, 1, v146
	s_waitcnt lgkmcnt(0)
	ds_write_b32 v145, v146
	s_sub_u32 s65, s6, 1
	s_mov_b32 s69, 0x100000

.Lsc_G_goz1:
	s_waitcnt vmcnt(0)
	v_lshlrev_b32_e32 v64, 16, v54
	v_and_b32_e32 v65, 0xffff0000, v54
	v_mul_f32_e32 v64, 0x3fb8aa3b, v64
	v_mul_f32_e32 v65, 0x3fb8aa3b, v65
	v_lshlrev_b32_e32 v66, 16, v55
	v_and_b32_e32 v67, 0xffff0000, v55
	v_mul_f32_e32 v66, 0x3fb8aa3b, v66
	v_mul_f32_e32 v67, 0x3fb8aa3b, v67
	v_lshlrev_b32_e32 v68, 16, v56
	v_and_b32_e32 v69, 0xffff0000, v56
	v_mul_f32_e32 v68, 0x3fb8aa3b, v68
	v_mul_f32_e32 v69, 0x3fb8aa3b, v69
	v_lshlrev_b32_e32 v70, 16, v57
	v_and_b32_e32 v71, 0xffff0000, v57
	v_mul_f32_e32 v70, 0x3fb8aa3b, v70
	v_mul_f32_e32 v71, 0x3fb8aa3b, v71
	ds_write_b128 v153, v[64:67]
	ds_write_b128 v153, v[68:71] offset:128
	s_waitcnt lgkmcnt(0)
	ds_read_b32 v124, v154 offset:0
	ds_read_b32 v125, v154 offset:256
	ds_read_b32 v126, v154 offset:512
	ds_read_b32 v127, v154 offset:768
	ds_read_b32 v128, v154 offset:1024
	ds_read_b32 v129, v154 offset:1280
	ds_read_b32 v130, v154 offset:1536
	ds_read_b32 v131, v154 offset:1792
	v_lshlrev_b32_e32 v108, 16, v50
	v_and_b32_e32 v109, 0xffff0000, v50
	v_lshlrev_b32_e32 v110, 16, v58
	v_and_b32_e32 v111, 0xffff0000, v58
	v_lshlrev_b32_e32 v96, 16, v46
	v_and_b32_e32 v97, 0xffff0000, v46
	v_pk_add_f32 v[112:113], v[110:111], -1.0 op_sel_hi:[1,0]
	v_pk_mul_f32 v[114:115], v[12:13], v[108:109]
	v_pk_fma_f32 v[112:113], v[20:21], v[112:113], 1.0 op_sel_hi:[1,1,0]
	v_pk_mul_f32 v[88:89], v[62:63], v[114:115] op_sel_hi:[0,1]
	v_pk_mul_f32 v[72:73], v[112:113], v[108:109]
	v_pk_mul_f32 v[80:81], v[88:89], v[110:111]
	v_lshlrev_b32_e32 v108, 16, v51
	v_and_b32_e32 v109, 0xffff0000, v51
	v_lshlrev_b32_e32 v110, 16, v59
	v_and_b32_e32 v111, 0xffff0000, v59
	v_lshlrev_b32_e32 v98, 16, v47
	v_and_b32_e32 v99, 0xffff0000, v47
	v_pk_add_f32 v[112:113], v[110:111], -1.0 op_sel_hi:[1,0]
	v_pk_mul_f32 v[114:115], v[14:15], v[108:109]
	v_pk_fma_f32 v[112:113], v[22:23], v[112:113], 1.0 op_sel_hi:[1,1,0]
	v_pk_mul_f32 v[90:91], v[62:63], v[114:115] op_sel_hi:[0,1]
	v_pk_mul_f32 v[74:75], v[112:113], v[108:109]
	v_pk_mul_f32 v[82:83], v[90:91], v[110:111]
	v_lshlrev_b32_e32 v108, 16, v52
	v_and_b32_e32 v109, 0xffff0000, v52
	v_lshlrev_b32_e32 v110, 16, v60
	v_and_b32_e32 v111, 0xffff0000, v60
	v_lshlrev_b32_e32 v100, 16, v48
	v_and_b32_e32 v101, 0xffff0000, v48
	v_pk_add_f32 v[112:113], v[110:111], -1.0 op_sel_hi:[1,0]
	v_pk_mul_f32 v[114:115], v[16:17], v[108:109]
	v_pk_fma_f32 v[112:113], v[24:25], v[112:113], 1.0 op_sel_hi:[1,1,0]
	v_pk_mul_f32 v[92:93], v[62:63], v[114:115] op_sel_hi:[0,1]
	v_pk_mul_f32 v[76:77], v[112:113], v[108:109]
	v_pk_mul_f32 v[84:85], v[92:93], v[110:111]
	v_lshlrev_b32_e32 v108, 16, v53
	v_and_b32_e32 v109, 0xffff0000, v53
	v_lshlrev_b32_e32 v110, 16, v61
	v_and_b32_e32 v111, 0xffff0000, v61
	v_lshlrev_b32_e32 v102, 16, v49
	v_and_b32_e32 v103, 0xffff0000, v49
	v_pk_add_f32 v[112:113], v[110:111], -1.0 op_sel_hi:[1,0]
	v_pk_mul_f32 v[114:115], v[18:19], v[108:109]
	v_pk_fma_f32 v[112:113], v[26:27], v[112:113], 1.0 op_sel_hi:[1,1,0]
	v_pk_mul_f32 v[94:95], v[62:63], v[114:115] op_sel_hi:[0,1]
	v_pk_mul_f32 v[78:79], v[112:113], v[108:109]
	v_pk_mul_f32 v[86:87], v[94:95], v[110:111]
	v_lshlrev_b32_e32 v104, 16, v63
	v_and_b32_e32 v105, 0xffff0000, v63
	s_waitcnt lgkmcnt(0)
	v_add_f32_e32 v125, v124, v125
	v_add_f32_e32 v126, v125, v126
	v_add_f32_e32 v127, v126, v127
	v_add_f32_e32 v128, v127, v128
	v_add_f32_e32 v129, v128, v129
	v_add_f32_e32 v130, v129, v130
	v_add_f32_e32 v131, v130, v131
	ds_write_b32 v155, v124 offset:0
	ds_write_b32 v155, v125 offset:256
	ds_write_b32 v155, v126 offset:512
	ds_write_b32 v155, v127 offset:768
	ds_write_b32 v155, v128 offset:1024
	ds_write_b32 v155, v129 offset:1280
	ds_write_b32 v155, v130 offset:1536
	ds_write_b32 v155, v131 offset:1792
	s_waitcnt lgkmcnt(0)
	ds_read_b128 v[116:119], v153 offset:2048
	ds_read_b128 v[120:123], v153 offset:2176
	s_waitcnt lgkmcnt(0)
	v_sub_f32_e32 v64, v64, v116
	v_exp_f32_e32 v124, v116
	v_exp_f32_e64 v116, -v116
	v_exp_f32_e32 v64, v64
	v_sub_f32_e32 v65, v65, v117
	v_exp_f32_e32 v125, v117
	v_exp_f32_e64 v117, -v117
	v_exp_f32_e32 v65, v65
	v_sub_f32_e32 v66, v66, v118
	v_exp_f32_e32 v126, v118
	v_exp_f32_e64 v118, -v118
	v_exp_f32_e32 v66, v66
	v_sub_f32_e32 v67, v67, v119
	v_exp_f32_e32 v127, v119
	v_exp_f32_e64 v119, -v119
	v_exp_f32_e32 v67, v67
	v_sub_f32_e32 v68, v68, v120
	v_exp_f32_e32 v128, v120
	v_exp_f32_e64 v120, -v120
	v_exp_f32_e32 v68, v68
	v_sub_f32_e32 v69, v69, v121
	v_exp_f32_e32 v129, v121
	v_exp_f32_e64 v121, -v121
	v_exp_f32_e32 v69, v69
	v_sub_f32_e32 v70, v70, v122
	v_exp_f32_e32 v130, v122
	v_exp_f32_e64 v122, -v122
	v_exp_f32_e32 v70, v70
	v_sub_f32_e32 v71, v71, v123
	v_exp_f32_e32 v131, v123
	v_exp_f32_e64 v123, -v123
	v_exp_f32_e32 v71, v71
	s_nop 1
	v_pk_mul_f32 v[72:73], v[72:73], v[124:125]
	v_pk_mul_f32 v[80:81], v[80:81], v[124:125]
	v_pk_mul_f32 v[88:89], v[88:89], v[64:65]
	v_pk_mul_f32 v[96:97], v[96:97], v[116:117]
	v_pk_mul_f32 v[74:75], v[74:75], v[126:127]
	v_pk_mul_f32 v[82:83], v[82:83], v[126:127]
	v_pk_mul_f32 v[90:91], v[90:91], v[66:67]
	v_pk_mul_f32 v[98:99], v[98:99], v[118:119]
	v_pk_mul_f32 v[76:77], v[76:77], v[128:129]
	v_pk_mul_f32 v[84:85], v[84:85], v[128:129]
	v_pk_mul_f32 v[92:93], v[92:93], v[68:69]
	v_pk_mul_f32 v[100:101], v[100:101], v[120:121]
	v_pk_mul_f32 v[78:79], v[78:79], v[130:131]
	v_pk_mul_f32 v[86:87], v[86:87], v[130:131]
	v_pk_mul_f32 v[94:95], v[94:95], v[70:71]
	v_pk_mul_f32 v[102:103], v[102:103], v[122:123]
	ds_write_b128 v8, v[72:75] offset:34816
	ds_write_b128 v8, v[76:79] offset:34944
	ds_write_b128 v8, v[80:83] offset:35072
	ds_write_b128 v8, v[84:87] offset:35200
	ds_write2_b32 v140, v96, v97 offset0:1 offset1:3
	ds_write2_b32 v141, v88, v89 offset0:0 offset1:2
	ds_write2_b32 v140, v98, v99 offset0:65 offset1:67
	ds_write2_b32 v141, v90, v91 offset0:64 offset1:66
	ds_write2_b32 v140, v100, v101 offset0:33 offset1:35
	ds_write2_b32 v141, v92, v93 offset0:32 offset1:34
	ds_write2_b32 v140, v102, v103 offset0:97 offset1:99
	ds_write2_b32 v141, v94, v95 offset0:96 offset1:98
	ds_write2_b32 v143, v104, v105 offset1:36
	s_and_saveexec_b64 s[68:69], s[12:13]
	ds_write_b128 v158, v[88:91] offset:34816
	ds_write_b128 v158, v[92:95] offset:34944
	s_mov_b64 exec, s[68:69]
	s_and_saveexec_b64 s[68:69], s[14:15]
	ds_write_b128 v159, v[116:119] offset:34816
	ds_write_b128 v159, v[120:123] offset:34944
	s_mov_b64 exec, s[68:69]
	ds_read_b128 v[120:123], v11 offset:16384
	ds_read_b128 v[124:127], v11 offset:16400
	ds_read_b128 v[128:131], v11 offset:16416
	ds_read_b128 v[132:135], v11 offset:16432
	s_waitcnt lgkmcnt(0)
	v_add_f32_e32 v120, v120, v121
	v_add_f32_e32 v122, v122, v123
	v_add_f32_e32 v124, v124, v125
	v_add_f32_e32 v126, v126, v127
	v_add_f32_e32 v120, v120, v122
	v_add_f32_e32 v124, v124, v126
	v_add_f32_e32 v136, v120, v124
	v_add_f32_e32 v128, v128, v129
	v_add_f32_e32 v130, v130, v131
	v_add_f32_e32 v132, v132, v133
	v_add_f32_e32 v134, v134, v135
	v_add_f32_e32 v128, v128, v130
	v_add_f32_e32 v132, v132, v134
	v_add_f32_e32 v137, v128, v132
	global_store_dwordx2 v7, v[136:137], s[48:49]
	v_add_u32_e32 v7, s64, v7
	s_add_i32 s6, s6, 1
	v_add_u32_e32 v146, 1, v146
	s_waitcnt lgkmcnt(0)
	ds_write_b32 v145, v146
	s_sub_u32 s65, s6, 1
	s_mov_b32 s69, 0x100000

.Lsc_G_goz2:
	ds_read_b128 v[120:123], v11 offset:0
	ds_read_b128 v[124:127], v11 offset:16
	ds_read_b128 v[128:131], v11 offset:32
	ds_read_b128 v[132:135], v11 offset:48
	s_waitcnt lgkmcnt(0)
	v_add_f32_e32 v120, v120, v121
	v_add_f32_e32 v122, v122, v123
	v_add_f32_e32 v124, v124, v125
	v_add_f32_e32 v126, v126, v127
	v_add_f32_e32 v120, v120, v122
	v_add_f32_e32 v124, v124, v126
	v_add_f32_e32 v136, v120, v124
	v_add_f32_e32 v128, v128, v129
	v_add_f32_e32 v130, v130, v131
	v_add_f32_e32 v132, v132, v133
	v_add_f32_e32 v134, v134, v135
	v_add_f32_e32 v128, v128, v130
	v_add_f32_e32 v132, v132, v134
	v_add_f32_e32 v137, v128, v132
	global_store_dwordx2 v7, v[136:137], s[48:49]
	v_add_u32_e32 v7, s64, v7
	s_add_i32 s6, s6, 1
	v_add_u32_e32 v146, 1, v146
	s_waitcnt lgkmcnt(0)
	ds_write_b32 v145, v146
	s_sub_u32 s65, s6, 1
	s_mov_b32 s69, 0x100000

.Lsc_G_goz3:
	ds_read_b128 v[120:123], v11 offset:16384
	ds_read_b128 v[124:127], v11 offset:16400
	ds_read_b128 v[128:131], v11 offset:16416
	ds_read_b128 v[132:135], v11 offset:16432
	s_waitcnt lgkmcnt(0)
	v_add_f32_e32 v120, v120, v121
	v_add_f32_e32 v122, v122, v123
	v_add_f32_e32 v124, v124, v125
	v_add_f32_e32 v126, v126, v127
	v_add_f32_e32 v120, v120, v122
	v_add_f32_e32 v124, v124, v126
	v_add_f32_e32 v136, v120, v124
	v_add_f32_e32 v128, v128, v129
	v_add_f32_e32 v130, v130, v131
	v_add_f32_e32 v132, v132, v133
	v_add_f32_e32 v134, v134, v135
	v_add_f32_e32 v128, v128, v130
	v_add_f32_e32 v132, v132, v134
	v_add_f32_e32 v137, v128, v132
	global_store_dwordx2 v7, v[136:137], s[48:49]
	v_add_u32_e32 v7, s64, v7
	s_add_i32 s6, s6, 1
	v_add_u32_e32 v146, 1, v146
	s_waitcnt lgkmcnt(0)
	ds_write_b32 v145, v146
